# plus attention epilogue: eight head-gain quads prefetched once behind the normalisation math instead of sixteen load-wait pairs
# baseline (speedup 1.0000x reference)
; __device__ __forceinline__ unsigned cvt_pk_bf16(float lo, float hi) { unsigned r; asm volatile("v_cvt_pk_bf16_f32 %0, %1, %2" : "=v"(r) : "v"(lo), "v"(hi)); return r; }
; template <int NQB> ...
;     ...
;     for (int qb = 0; qb < NQB; ++qb) {
;         float l = lrun[qb]; l += __shfl_xor(l, 32);
;         const float inv = 1.0f / l; float ss = 0.f;
; #pragma unroll
;         for (int db = 0; db < 2; ++db)
; #pragma unroll
;             for (int i = 0; i < 16; ++i) { const float v = o[db][qb][i] * inv; o[db][qb][i] = v; ss += v * v; }
;         ss += __shfl_xor(ss, 32);
;         const float rn = rsqrtf(ss * (1.0f / 64.0f) + EPS);
;         const int q = 32 * qb + r2;
;         if (q < nq) {
; #pragma unroll
;             for (int db = 0; db < 2; ++db)
; #pragma unroll
;                 for (int g4 = 0; g4 < 4; ++g4) {
;                     const unsigned d0 = 32 * db + 8 * g4 + 4 * h2;
;                     const f32x4 gg = *(const f32x4*)(gvec + d0);
;                     u32x2 w; w.x = cvt_pk_bf16(o[db][qb][4 * g4 + 0] * rn * gg[0], o[db][qb][4 * g4 + 1] * rn * gg[1]);
;                     w.y = cvt_pk_bf16(o[db][qb][4 * g4 + 2] * rn * gg[2], o[db][qb][4 * g4 + 3] * rn * gg[3]);
;                     *(u32x2*)(outp + (unsigned)(q * DM + d0)) = w;
;                 }
.LBB0_570:
	v_and_b32_e32 v67, 64, v208
	v_xor_b32_e32 v64, 32, v208
	v_add_u32_e32 v67, 64, v67
	v_cmp_lt_i32_e32 vcc, v64, v67
	s_ashr_i32 s79, s78, 31
	s_lshl_b64 s[2:3], s[78:79], 11
	v_cndmask_b32_e32 v64, v208, v64, vcc
	v_lshlrev_b32_e32 v67, 2, v64
	v_readlane_b32 s4, v255, 33
	ds_bpermute_b32 v64, v67, v65
	s_add_u32 s2, s4, s2
	v_readlane_b32 s4, v255, 35
	s_addc_u32 s3, s4, s3
	s_waitcnt lgkmcnt(0)
	s_add_u32 s6, s72, s0
	s_addc_u32 s7, s73, s1
	s_lshl_b64 s[4:5], s[96:97], 2
	s_add_u32 s4, s6, s4
	v_add_f32_e32 v65, v65, v64
	s_addc_u32 s5, s7, s5
	v_lshrrev_b32_e32 v128, 5, v212
	v_lshlrev_b32_e32 v128, 4, v128
	v_mov_b32_e32 v129, 0
	v_lshl_add_u64 v[128:129], v[128:129], 0, s[4:5]
	global_load_dwordx4 v[96:99], v[128:129], off
	global_load_dwordx4 v[100:103], v[128:129], off offset:32
	global_load_dwordx4 v[104:107], v[128:129], off offset:64
	global_load_dwordx4 v[108:111], v[128:129], off offset:96
	global_load_dwordx4 v[112:115], v[128:129], off offset:128
	global_load_dwordx4 v[116:119], v[128:129], off offset:160
	global_load_dwordx4 v[120:123], v[128:129], off offset:192
	global_load_dwordx4 v[124:127], v[128:129], off offset:224
	v_div_scale_f32 v69, s[6:7], v65, v65, 1.0
	v_rcp_f32_e32 v70, v69
	s_nop 0
	v_ashrrev_i32_e32 v64, 3, v212
	v_fma_f32 v71, -v69, v70, 1.0
	v_fmac_f32_e32 v70, v71, v70
	v_div_scale_f32 v71, vcc, 1.0, v65, 1.0
	v_mul_f32_e32 v72, v71, v70
	v_fma_f32 v73, -v69, v72, v71
	v_fmac_f32_e32 v72, v73, v70
	v_fma_f32 v69, -v69, v72, v71
	v_div_fmas_f32 v69, v69, v70, v72
	v_div_fixup_f32 v65, v69, v65, 1.0
	v_mul_f32_e32 v79, v49, v65
	v_mul_f32_e32 v78, v48, v65
	v_mul_f32_e32 v82, v79, v79
	v_fmac_f32_e32 v82, v78, v78
	v_mul_f32_e32 v80, v50, v65
	v_fmac_f32_e32 v82, v80, v80
	v_mul_f32_e32 v81, v51, v65
	v_fmac_f32_e32 v82, v81, v81
	v_mul_f32_e32 v74, v52, v65
	v_fmac_f32_e32 v82, v74, v74
	v_mul_f32_e32 v75, v53, v65
	v_fmac_f32_e32 v82, v75, v75
	v_mul_f32_e32 v76, v54, v65
	v_fmac_f32_e32 v82, v76, v76
	v_mul_f32_e32 v77, v55, v65
	v_fmac_f32_e32 v82, v77, v77
	v_mul_f32_e32 v70, v56, v65
	v_fmac_f32_e32 v82, v70, v70
	v_mul_f32_e32 v71, v57, v65
	v_fmac_f32_e32 v82, v71, v71
	v_mul_f32_e32 v72, v58, v65
	v_fmac_f32_e32 v82, v72, v72
	v_mul_f32_e32 v73, v59, v65
	v_fmac_f32_e32 v82, v73, v73
	v_mul_f32_e32 v69, v60, v65
	v_fmac_f32_e32 v82, v69, v69
	v_mul_f32_e32 v61, v61, v65
	v_fmac_f32_e32 v82, v61, v61
	v_mul_f32_e32 v62, v62, v65
	v_fmac_f32_e32 v82, v62, v62
	v_mul_f32_e32 v63, v63, v65
	v_fmac_f32_e32 v82, v63, v63
	v_mul_f32_e32 v58, v32, v65
	v_fmac_f32_e32 v82, v58, v58
	v_mul_f32_e32 v59, v33, v65
	v_fmac_f32_e32 v82, v59, v59
	v_mul_f32_e32 v60, v34, v65
	v_fmac_f32_e32 v82, v60, v60
	v_mul_f32_e32 v35, v35, v65
	v_fmac_f32_e32 v82, v35, v35
	v_mul_f32_e32 v33, v36, v65
	v_fmac_f32_e32 v82, v33, v33
	v_mul_f32_e32 v55, v37, v65
	v_fmac_f32_e32 v82, v55, v55
	v_mul_f32_e32 v56, v38, v65
	v_fmac_f32_e32 v82, v56, v56
	v_mul_f32_e32 v57, v39, v65
	v_fmac_f32_e32 v82, v57, v57
	v_mul_f32_e32 v51, v40, v65
	v_fmac_f32_e32 v82, v51, v51
	v_mul_f32_e32 v52, v41, v65
	v_fmac_f32_e32 v82, v52, v52
	v_mul_f32_e32 v53, v42, v65
	v_fmac_f32_e32 v82, v53, v53
	v_mul_f32_e32 v54, v43, v65
	v_fmac_f32_e32 v82, v54, v54
	v_mul_f32_e32 v48, v44, v65
	v_fmac_f32_e32 v82, v48, v48
	v_mul_f32_e32 v49, v45, v65
	v_fmac_f32_e32 v82, v49, v49
	v_mul_f32_e32 v46, v46, v65
	v_fmac_f32_e32 v82, v46, v46
	v_mul_f32_e32 v47, v47, v65
	v_fmac_f32_e32 v82, v47, v47
	ds_bpermute_b32 v37, v67, v82
	v_and_b32_e32 v68, 31, v212
	v_and_b32_e32 v64, -4, v64
	v_cmp_gt_u32_e32 vcc, s76, v68
	v_add_u32_e32 v44, 8, v64
	v_add_u32_e32 v42, 16, v64
	v_add_u32_e32 v40, 24, v64
	v_add_u32_e32 v38, 32, v64
	v_add_u32_e32 v36, 40, v64
	v_add_u32_e32 v34, 48, v64
	v_add_u32_e32 v32, 56, v64
	s_waitcnt vmcnt(0)
	s_and_saveexec_b64 s[6:7], vcc
	s_cbranch_execz .LBB0_572
	v_mov_b32_e32 v65, v189
	v_lshl_add_u64 v[84:85], v[64:65], 2, s[4:5]
	s_waitcnt lgkmcnt(0)
	v_add_f32_e32 v37, v82, v37
	v_fmamk_f32 v37, v37, 0x3c800000, v190
	v_mul_f32_e32 v39, 0x4b800000, v37
	v_cmp_gt_f32_e32 vcc, s93, v37
	v_lshlrev_b32_e32 v50, 10, v68
	v_mov_b32_e32 v45, v189
	v_cndmask_b32_e32 v37, v37, v39, vcc
	v_rsq_f32_e32 v37, v37
	v_mov_b32_e32 v83, v189
	v_add_u32_e32 v82, v64, v50
	v_lshl_add_u64 v[88:89], v[44:45], 2, s[4:5]
	v_mul_f32_e32 v39, 0x45800000, v37
	v_cndmask_b32_e32 v45, v37, v39, vcc
	v_lshl_add_u64 v[82:83], v[82:83], 1, s[2:3]
	v_mul_f32_e32 v37, v78, v45
	v_mul_f32_e32 v39, v79, v45
	v_mul_f32_e32 v41, v80, v45
	v_mul_f32_e32 v43, v81, v45
	v_mul_f32_e32 v35, v35, v45
	v_mul_f32_e32 v33, v33, v45
	v_mul_f32_e32 v37, v37, v96
	v_mul_f32_e32 v39, v39, v97
	v_mul_f32_e32 v41, v41, v98
	v_mul_f32_e32 v43, v43, v99
	v_cvt_pk_bf16_f32 v78, v37, v39
	v_cvt_pk_bf16_f32 v79, v41, v43
	global_store_dwordx2 v[82:83], v[78:79], off
	v_mov_b32_e32 v83, v189
	v_mov_b32_e32 v43, v189
	v_add_u32_e32 v82, v44, v50
	v_lshl_add_u64 v[84:85], v[42:43], 2, s[4:5]
	v_lshl_add_u64 v[82:83], v[82:83], 1, s[2:3]
	v_mul_f32_e32 v37, v74, v45
	v_mul_f32_e32 v39, v75, v45
	v_mul_f32_e32 v41, v76, v45
	v_mul_f32_e32 v43, v77, v45
	v_mul_f32_e32 v37, v37, v100
	v_mul_f32_e32 v39, v39, v101
	v_mul_f32_e32 v41, v41, v102
	v_mul_f32_e32 v43, v43, v103
	v_cvt_pk_bf16_f32 v74, v37, v39
	v_cvt_pk_bf16_f32 v75, v41, v43
	global_store_dwordx2 v[82:83], v[74:75], off
	v_mov_b32_e32 v79, v189
	v_mov_b32_e32 v41, v189
	v_add_u32_e32 v78, v42, v50
	v_lshl_add_u64 v[80:81], v[40:41], 2, s[4:5]
	v_lshl_add_u64 v[78:79], v[78:79], 1, s[2:3]
	v_mul_f32_e32 v37, v70, v45
	v_mul_f32_e32 v39, v71, v45
	v_mul_f32_e32 v41, v72, v45
	v_mul_f32_e32 v43, v73, v45
; __device__ __forceinline__ unsigned cvt_pk_bf16(float lo, float hi) { unsigned r; asm volatile("v_cvt_pk_bf16_f32 %0, %1, %2" : "=v"(r) : "v"(lo), "v"(hi)); return r; }
; template <int NQB> ...
;     ...
; #pragma unroll
;             for (int db = 0; db < 2; ++db)
; #pragma unroll
;                 for (int g4 = 0; g4 < 4; ++g4) {
;                     const unsigned d0 = 32 * db + 8 * g4 + 4 * h2;
;                     const f32x4 gg = *(const f32x4*)(gvec + d0);
;                     u32x2 w; w.x = cvt_pk_bf16(o[db][qb][4 * g4 + 0] * rn * gg[0], o[db][qb][4 * g4 + 1] * rn * gg[1]);
;                     w.y = cvt_pk_bf16(o[db][qb][4 * g4 + 2] * rn * gg[2], o[db][qb][4 * g4 + 3] * rn * gg[3]);
;                     *(u32x2*)(outp + (unsigned)(q * DM + d0)) = w;
;                 }
	v_mul_f32_e32 v37, v37, v104
	v_mul_f32_e32 v39, v39, v105
	v_mul_f32_e32 v41, v41, v106
	v_mul_f32_e32 v43, v43, v107
	v_cvt_pk_bf16_f32 v70, v37, v39
	v_cvt_pk_bf16_f32 v71, v41, v43
	global_store_dwordx2 v[78:79], v[70:71], off
	v_mov_b32_e32 v75, v189
	v_mov_b32_e32 v39, v189
	v_add_u32_e32 v74, v40, v50
	v_lshl_add_u64 v[76:77], v[38:39], 2, s[4:5]
	v_lshl_add_u64 v[74:75], v[74:75], 1, s[2:3]
	v_mul_f32_e32 v37, v69, v45
	v_mul_f32_e32 v39, v61, v45
	v_mul_f32_e32 v41, v62, v45
	v_mul_f32_e32 v43, v63, v45
	v_mul_f32_e32 v37, v37, v108
	v_mul_f32_e32 v39, v39, v109
	v_mul_f32_e32 v41, v41, v110
	v_mul_f32_e32 v43, v43, v111
	v_cvt_pk_bf16_f32 v62, v37, v39
	v_cvt_pk_bf16_f32 v63, v41, v43
	global_store_dwordx2 v[74:75], v[62:63], off
	v_mov_b32_e32 v63, v189
	v_mov_b32_e32 v37, v189
	v_add_u32_e32 v62, v38, v50
	v_lshl_add_u64 v[74:75], v[36:37], 2, s[4:5]
	v_lshl_add_u64 v[62:63], v[62:63], 1, s[2:3]
	v_mul_f32_e32 v37, v58, v45
	v_mul_f32_e32 v39, v59, v45
	v_mul_f32_e32 v41, v60, v45
	v_mul_f32_e32 v37, v37, v112
	v_mul_f32_e32 v39, v39, v113
	v_mul_f32_e32 v41, v41, v114
	v_mul_f32_e32 v35, v35, v115
	v_cvt_pk_bf16_f32 v58, v37, v39
	v_cvt_pk_bf16_f32 v59, v41, v35
	global_store_dwordx2 v[62:63], v[58:59], off
	v_mov_b32_e32 v63, v189
	v_mov_b32_e32 v35, v189
	v_add_u32_e32 v62, v36, v50
	v_lshl_add_u64 v[70:71], v[34:35], 2, s[4:5]
	v_lshl_add_u64 v[62:63], v[62:63], 1, s[2:3]
	v_mul_f32_e32 v35, v55, v45
	v_mul_f32_e32 v37, v56, v45
	v_mul_f32_e32 v39, v57, v45
	v_mul_f32_e32 v33, v33, v116
	v_mul_f32_e32 v35, v35, v117
	v_mul_f32_e32 v37, v37, v118
	v_mul_f32_e32 v39, v39, v119
	v_cvt_pk_bf16_f32 v56, v33, v35
	v_cvt_pk_bf16_f32 v57, v37, v39
	global_store_dwordx2 v[62:63], v[56:57], off
	v_mov_b32_e32 v61, v189
	v_mov_b32_e32 v33, v189
	v_add_u32_e32 v60, v34, v50
	v_lshl_add_u64 v[62:63], v[32:33], 2, s[4:5]
	v_lshl_add_u64 v[60:61], v[60:61], 1, s[2:3]
	v_mul_f32_e32 v33, v51, v45
	v_mul_f32_e32 v35, v52, v45
	v_mul_f32_e32 v37, v53, v45
	v_mul_f32_e32 v39, v54, v45
	v_mov_b32_e32 v51, v189
	v_add_u32_e32 v50, v32, v50
	v_mul_f32_e32 v33, v33, v120
	v_mul_f32_e32 v35, v35, v121
	v_mul_f32_e32 v37, v37, v122
	v_mul_f32_e32 v39, v39, v123
	v_cvt_pk_bf16_f32 v52, v33, v35
	v_cvt_pk_bf16_f32 v53, v37, v39
	global_store_dwordx2 v[60:61], v[52:53], off
	v_mul_f32_e32 v33, v48, v45
	v_mul_f32_e32 v35, v49, v45
	v_mul_f32_e32 v37, v46, v45
	v_mul_f32_e32 v39, v47, v45
	v_lshl_add_u64 v[48:49], v[50:51], 1, s[2:3]
	v_mul_f32_e32 v33, v33, v124
	v_mul_f32_e32 v35, v35, v125
	v_mul_f32_e32 v37, v37, v126
	v_mul_f32_e32 v39, v39, v127
	v_cvt_pk_bf16_f32 v46, v33, v35
	v_cvt_pk_bf16_f32 v47, v37, v39
	global_store_dwordx2 v[48:49], v[46:47], off
; __device__ __forceinline__ unsigned cvt_pk_bf16(float lo, float hi) { unsigned r; asm volatile("v_cvt_pk_bf16_f32 %0, %1, %2" : "=v"(r) : "v"(lo), "v"(hi)); return r; }
; template <int NQB> ...
;     ...
;     for (int qb = 0; qb < NQB; ++qb) {
;         float l = lrun[qb]; l += __shfl_xor(l, 32);
;         const float inv = 1.0f / l; float ss = 0.f;
; #pragma unroll
;         for (int db = 0; db < 2; ++db)
; #pragma unroll
;             for (int i = 0; i < 16; ++i) { const float v = o[db][qb][i] * inv; o[db][qb][i] = v; ss += v * v; }
;         ss += __shfl_xor(ss, 32);
;         const float rn = rsqrtf(ss * (1.0f / 64.0f) + EPS);
;         const int q = 32 * qb + r2;
;         if (q < nq) {
; #pragma unroll
;             for (int db = 0; db < 2; ++db)
; #pragma unroll
;                 for (int g4 = 0; g4 < 4; ++g4) {
;                     const unsigned d0 = 32 * db + 8 * g4 + 4 * h2;
;                     const f32x4 gg = *(const f32x4*)(gvec + d0);
;                     u32x2 w; w.x = cvt_pk_bf16(o[db][qb][4 * g4 + 0] * rn * gg[0], o[db][qb][4 * g4 + 1] * rn * gg[1]);
;                     w.y = cvt_pk_bf16(o[db][qb][4 * g4 + 2] * rn * gg[2], o[db][qb][4 * g4 + 3] * rn * gg[3]);
;                     *(u32x2*)(outp + (unsigned)(q * DM + d0)) = w;
;                 }
.LBB0_572:
	s_or_b64 exec, exec, s[6:7]
	ds_bpermute_b32 v33, v67, v66
	s_waitcnt lgkmcnt(0)
	v_add_f32_e32 v33, v66, v33
	v_div_scale_f32 v35, s[6:7], v33, v33, 1.0
	v_rcp_f32_e32 v37, v35
	v_div_scale_f32 v39, vcc, 1.0, v33, 1.0
	v_fma_f32 v41, -v35, v37, 1.0
	v_fmac_f32_e32 v37, v41, v37
	v_mul_f32_e32 v41, v39, v37
	v_fma_f32 v43, -v35, v41, v39
	v_fmac_f32_e32 v41, v43, v37
	v_fma_f32 v35, -v35, v41, v39
	v_div_fmas_f32 v35, v35, v37, v41
	v_div_fixup_f32 v52, v35, v33, 1.0
	v_mul_f32_e32 v49, v17, v52
	v_mul_f32_e32 v43, v16, v52
	v_mul_f32_e32 v45, v49, v49
	v_mul_f32_e32 v50, v18, v52
	v_fmac_f32_e32 v45, v43, v43
	v_mul_f32_e32 v51, v19, v52
	v_fmac_f32_e32 v45, v50, v50
	v_fmac_f32_e32 v45, v51, v51
	v_mul_f32_e32 v41, v20, v52
	v_fmac_f32_e32 v45, v41, v41
	v_mul_f32_e32 v46, v21, v52
	v_fmac_f32_e32 v45, v46, v46
	v_mul_f32_e32 v47, v22, v52
	v_fmac_f32_e32 v45, v47, v47
	v_mul_f32_e32 v48, v23, v52
	v_fmac_f32_e32 v45, v48, v48
	v_mul_f32_e32 v33, v24, v52
	v_fmac_f32_e32 v45, v33, v33
	v_mul_f32_e32 v35, v25, v52
	v_fmac_f32_e32 v45, v35, v35
	v_mul_f32_e32 v37, v26, v52
	v_fmac_f32_e32 v45, v37, v37
	v_mul_f32_e32 v39, v27, v52
	v_fmac_f32_e32 v45, v39, v39
	v_mul_f32_e32 v24, v28, v52
	v_fmac_f32_e32 v45, v24, v24
	v_mul_f32_e32 v25, v29, v52
	v_fmac_f32_e32 v45, v25, v25
	v_mul_f32_e32 v26, v30, v52
	v_fmac_f32_e32 v45, v26, v26
	v_mul_f32_e32 v27, v31, v52
	v_fmac_f32_e32 v45, v27, v27
	v_mul_f32_e32 v20, v0, v52
	v_fmac_f32_e32 v45, v20, v20
	v_mul_f32_e32 v21, v1, v52
	v_fmac_f32_e32 v45, v21, v21
	v_mul_f32_e32 v22, v2, v52
	v_fmac_f32_e32 v45, v22, v22
	v_mul_f32_e32 v23, v3, v52
	v_fmac_f32_e32 v45, v23, v23
	v_mul_f32_e32 v16, v4, v52
	v_fmac_f32_e32 v45, v16, v16
	v_mul_f32_e32 v17, v5, v52
	v_fmac_f32_e32 v45, v17, v17
	v_mul_f32_e32 v18, v6, v52
	v_fmac_f32_e32 v45, v18, v18
	v_mul_f32_e32 v19, v7, v52
	v_fmac_f32_e32 v45, v19, v19
	v_mul_f32_e32 v5, v8, v52
	v_fmac_f32_e32 v45, v5, v5
	v_mul_f32_e32 v6, v9, v52
	v_fmac_f32_e32 v45, v6, v6
	v_mul_f32_e32 v7, v10, v52
	v_fmac_f32_e32 v45, v7, v7
	v_mul_f32_e32 v8, v11, v52
	v_fmac_f32_e32 v45, v8, v8
	v_mul_f32_e32 v0, v12, v52
	v_fmac_f32_e32 v45, v0, v0
	v_mul_f32_e32 v1, v13, v52
	v_fmac_f32_e32 v45, v1, v1
	v_mul_f32_e32 v2, v14, v52
	v_fmac_f32_e32 v45, v2, v2
	v_mul_f32_e32 v3, v15, v52
	v_fmac_f32_e32 v45, v3, v3
	ds_bpermute_b32 v4, v67, v45
	v_or_b32_e32 v9, 32, v68
	v_cmp_gt_u32_e32 vcc, s76, v9
	s_and_saveexec_b64 s[6:7], vcc
	s_xor_b64 s[6:7], exec, s[6:7]
	s_cbranch_execz .LBB0_532
	v_mov_b32_e32 v65, v189
	v_lshl_add_u64 v[10:11], v[64:65], 2, s[4:5]
	s_waitcnt lgkmcnt(0)
	v_add_f32_e32 v14, v45, v4
	v_lshlrev_b32_e32 v4, 10, v9
	v_fmamk_f32 v9, v14, 0x3c800000, v190
	v_mul_f32_e32 v14, 0x4b800000, v9
	v_cmp_gt_f32_e32 vcc, s93, v9
	v_mov_b32_e32 v15, v189
	v_mov_b32_e32 v45, v189
	v_cndmask_b32_e32 v9, v9, v14, vcc
	v_rsq_f32_e32 v9, v9
	v_add_u32_e32 v14, v4, v64
	v_lshl_add_u64 v[28:29], v[44:45], 2, s[4:5]
	v_lshl_add_u64 v[14:15], v[14:15], 1, s[2:3]
	v_mul_f32_e32 v30, 0x45800000, v9
	v_cndmask_b32_e32 v9, v9, v30, vcc
	v_mul_f32_e32 v30, v43, v9
	v_mul_f32_e32 v31, v49, v9
	v_mul_f32_e32 v43, v50, v9
	v_mul_f32_e32 v45, v51, v9
	v_mul_f32_e32 v24, v24, v9
	v_mul_f32_e32 v25, v25, v9
	v_mul_f32_e32 v26, v26, v9
	v_mul_f32_e32 v27, v27, v9
	v_mul_f32_e32 v20, v20, v9
	v_mul_f32_e32 v21, v21, v9
	v_mul_f32_e32 v22, v22, v9
	v_mul_f32_e32 v23, v23, v9
	v_mul_f32_e32 v16, v16, v9
	v_mul_f32_e32 v17, v17, v9
	v_mul_f32_e32 v18, v18, v9
	v_mul_f32_e32 v19, v19, v9
	v_mul_f32_e32 v6, v6, v9
	v_mul_f32_e32 v7, v7, v9
	v_mul_f32_e32 v5, v5, v9
	v_mul_f32_e32 v8, v8, v9
	v_mul_f32_e32 v0, v0, v9
	v_mul_f32_e32 v1, v1, v9
	v_mul_f32_e32 v2, v2, v9
	v_mul_f32_e32 v3, v3, v9
	v_mul_f32_e32 v10, v30, v96
	v_mul_f32_e32 v11, v31, v97
	v_mul_f32_e32 v12, v43, v98
	v_mul_f32_e32 v13, v45, v99
	v_cvt_pk_bf16_f32 v10, v10, v11
	v_cvt_pk_bf16_f32 v11, v12, v13
	global_store_dwordx2 v[14:15], v[10:11], off
	v_mov_b32_e32 v15, v189
	v_mov_b32_e32 v43, v189
	v_add_u32_e32 v14, v44, v4
	v_mul_f32_e32 v30, v41, v9
	v_mul_f32_e32 v31, v46, v9
	v_lshl_add_u64 v[28:29], v[42:43], 2, s[4:5]
	v_lshl_add_u64 v[14:15], v[14:15], 1, s[2:3]
	v_mul_f32_e32 v41, v47, v9
	v_mul_f32_e32 v43, v48, v9
	v_mul_f32_e32 v10, v30, v100
	v_mul_f32_e32 v11, v31, v101
	v_mul_f32_e32 v12, v41, v102
	v_mul_f32_e32 v13, v43, v103
	v_cvt_pk_bf16_f32 v10, v10, v11
	v_cvt_pk_bf16_f32 v11, v12, v13
	global_store_dwordx2 v[14:15], v[10:11], off
	v_mov_b32_e32 v15, v189
	v_add_u32_e32 v14, v42, v4
	v_mul_f32_e32 v30, v33, v9
	v_mul_f32_e32 v31, v35, v9
	v_mov_b32_e32 v41, v189
	v_lshl_add_u64 v[14:15], v[14:15], 1, s[2:3]
	v_mul_f32_e32 v33, v37, v9
	v_mul_f32_e32 v35, v39, v9
	v_lshl_add_u64 v[28:29], v[40:41], 2, s[4:5]
	v_mov_b32_e32 v39, v189
	v_mov_b32_e32 v37, v189
	v_mul_f32_e32 v10, v30, v104
	v_mul_f32_e32 v11, v31, v105
	v_mul_f32_e32 v12, v33, v106
	v_mul_f32_e32 v13, v35, v107
	v_cvt_pk_bf16_f32 v10, v10, v11
	v_cvt_pk_bf16_f32 v11, v12, v13
	global_store_dwordx2 v[14:15], v[10:11], off
	v_mov_b32_e32 v15, v189
	v_add_u32_e32 v14, v40, v4
	v_lshl_add_u64 v[14:15], v[14:15], 1, s[2:3]
	v_lshl_add_u64 v[28:29], v[38:39], 2, s[4:5]
	v_mov_b32_e32 v35, v189
	v_mov_b32_e32 v33, v189
	v_mul_f32_e32 v10, v24, v108
	v_mul_f32_e32 v11, v25, v109
	v_mul_f32_e32 v12, v26, v110
	v_mul_f32_e32 v13, v27, v111
	v_cvt_pk_bf16_f32 v10, v10, v11
	v_cvt_pk_bf16_f32 v11, v12, v13
	global_store_dwordx2 v[14:15], v[10:11], off
	v_mov_b32_e32 v15, v189
	v_add_u32_e32 v14, v38, v4
	v_lshl_add_u64 v[14:15], v[14:15], 1, s[2:3]
	v_lshl_add_u64 v[24:25], v[36:37], 2, s[4:5]
	v_mul_f32_e32 v10, v20, v112
	v_mul_f32_e32 v11, v21, v113
	v_mul_f32_e32 v12, v22, v114
	v_mul_f32_e32 v13, v23, v115
	v_cvt_pk_bf16_f32 v10, v10, v11
	v_cvt_pk_bf16_f32 v11, v12, v13
	global_store_dwordx2 v[14:15], v[10:11], off
	v_mov_b32_e32 v15, v189
	v_add_u32_e32 v14, v36, v4
	v_lshl_add_u64 v[14:15], v[14:15], 1, s[2:3]
	v_lshl_add_u64 v[20:21], v[34:35], 2, s[4:5]
	v_mul_f32_e32 v10, v16, v116
	v_mul_f32_e32 v11, v17, v117
	v_mul_f32_e32 v12, v18, v118
	v_mul_f32_e32 v13, v19, v119
	v_cvt_pk_bf16_f32 v10, v10, v11
	v_cvt_pk_bf16_f32 v11, v12, v13
	global_store_dwordx2 v[14:15], v[10:11], off
	v_mov_b32_e32 v15, v189
	v_add_u32_e32 v14, v34, v4
	v_lshl_add_u64 v[14:15], v[14:15], 1, s[2:3]
	v_lshl_add_u64 v[16:17], v[32:33], 2, s[4:5]
	v_add_u32_e32 v4, v32, v4
	v_mul_f32_e32 v6, v6, v121
	v_mul_f32_e32 v7, v7, v122
	v_mul_f32_e32 v5, v5, v120
	v_mul_f32_e32 v8, v8, v123
	v_cvt_pk_bf16_f32 v6, v5, v6
	v_cvt_pk_bf16_f32 v7, v7, v8
	global_store_dwordx2 v[14:15], v[6:7], off
	v_mov_b32_e32 v5, v189
	v_mul_f32_e32 v0, v0, v124
	v_mul_f32_e32 v1, v1, v125
	v_mul_f32_e32 v2, v2, v126
	v_mul_f32_e32 v3, v3, v127
	v_cvt_pk_bf16_f32 v0, v0, v1
	v_cvt_pk_bf16_f32 v1, v2, v3
	v_lshl_add_u64 v[2:3], v[4:5], 1, s[2:3]
	global_store_dwordx2 v[2:3], v[0:1], off
	s_branch .LBB0_532
